# attention phase: one static s_setprio 1 for second-slot workgroups (blockIdx bit 8), reset after the phase (strategy 7.4)
# baseline (speedup 1.0000x reference)
.LBB0_961:
	s_or_b64 exec, exec, s[8:9]
	v_mov_b32_e32 v113, 0
	s_waitcnt lgkmcnt(0)
	s_barrier
	s_bitcmp1_b32 s2, 8
	s_cbranch_scc0 .Lprio_attn_skip
	s_setprio 1
.Lprio_attn_skip:
	s_and_saveexec_b64 s[8:9], s[4:5]
	s_cbranch_execz .LBB0_965
	s_mov_b64 s[12:13], exec
	v_mbcnt_lo_u32_b32 v0, s12, 0
	v_mbcnt_hi_u32_b32 v0, s13, v0
	v_cmp_eq_u32_e32 vcc, 0, v0
	s_and_saveexec_b64 s[10:11], vcc
	s_cbranch_execz .LBB0_964
	s_load_dwordx2 s[0:1], s[76:77], 0x138
	s_lshl_b32 s3, s84, 2
	s_bcnt1_i32_b64 s6, s[12:13]
	v_mov_b32_e32 v1, s3
	v_mov_b32_e32 v2, s6
	s_waitcnt lgkmcnt(0)
	global_atomic_add v1, v1, v2, s[0:1] sc0

.LBB0_1066:
	s_waitcnt vmcnt(0)
	s_barrier
	s_setprio 0
	s_and_saveexec_b64 s[10:11], s[4:5]
	v_readlane_b32 s52, v255, 8
	v_readlane_b32 s54, v255, 0
	v_readlane_b32 s58, v255, 4
	v_readlane_b32 s53, v255, 9
	v_readlane_b32 s55, v255, 1
	v_readlane_b32 s56, v255, 6
	v_readlane_b32 s59, v255, 5
	v_readlane_b32 s57, v255, 3
	v_readlane_b32 s61, v255, 7
	s_cbranch_execz .LBB0_1118
	v_mov_b32_e32 v0, 0x12000
	s_waitcnt vmcnt(0) expcnt(0) lgkmcnt(0)
	ds_read_b32 v2, v0
	v_mov_b32_e32 v0, 0x12004
	ds_read_b32 v0, v0
	s_waitcnt lgkmcnt(1)
	v_cmp_ne_u32_e32 vcc, 0, v2
	s_cbranch_vccnz .LBB0_1082
	s_add_u32 s12, s82, 0x1000
	s_addc_u32 s13, s83, 0
	s_add_u32 s14, s82, 0x1100
	s_addc_u32 s15, s83, 0
	s_add_u32 s16, s82, 0x1200
	s_addc_u32 s17, s83, 0
	s_mul_i32 s0, s59, s57
	s_add_u32 s18, s82, 0x1300
	s_mul_i32 s0, s0, s58
	s_addc_u32 s19, s83, 0
	s_mov_b32 s1, 1
	v_mov_b32_e32 v16, 0
	s_branch .LBB0_1070
